# spatial item loop: next-item register hand-over moves deferred behind the existing vmcnt(8) at the end of the item so the prefetched loads overlap the whole item
# speedup vs baseline: 1.0028x; 1.0028x over previous
.LBB0_59:
	v_lshlrev_b32_e32 v16, 16, v140
	v_fma_f32 v17, v32, v40, v138
	v_mul_f32_e32 v32, v17, v16
	v_and_b32_e32 v16, 0xffff0000, v140
	v_fma_f32 v17, v33, v41, v138
	v_mul_f32_e32 v33, v17, v16
	v_lshlrev_b32_e32 v16, 16, v141
	v_fma_f32 v17, v34, v42, v138
	v_mul_f32_e32 v34, v17, v16
	v_and_b32_e32 v16, 0xffff0000, v141
	v_fma_f32 v17, v35, v43, v138
	v_mul_f32_e32 v35, v17, v16
	v_mul_f32_e32 v16, v33, v33
	v_mul_f32_e32 v17, v34, v34
	v_fmac_f32_e32 v16, v32, v32
	v_fmac_f32_e32 v17, v35, v35
	v_add_f32_e32 v16, v16, v17
	v_lshlrev_b32_e32 v17, 16, v136
	v_fma_f32 v18, v36, v52, v138
	v_mul_f32_e32 v36, v18, v17
	v_and_b32_e32 v17, 0xffff0000, v136
	v_fma_f32 v18, v37, v53, v138
	v_mul_f32_e32 v37, v18, v17
	v_lshlrev_b32_e32 v17, 16, v137
	v_fma_f32 v18, v38, v54, v138
	v_mul_f32_e32 v38, v18, v17
	v_and_b32_e32 v17, 0xffff0000, v137
	v_fma_f32 v18, v39, v55, v138
	v_mul_f32_e32 v39, v18, v17
	v_mul_f32_e32 v17, v37, v37
	v_mul_f32_e32 v18, v38, v38
	v_fmac_f32_e32 v17, v36, v36
	v_fmac_f32_e32 v18, v39, v39
	v_add_f32_e32 v17, v17, v18
	v_add_f32_e32 v16, v16, v17
	v_lshlrev_b32_e32 v17, 16, v134
	v_fma_f32 v18, v44, v60, v138
	v_mul_f32_e32 v40, v18, v17
	v_and_b32_e32 v17, 0xffff0000, v134
	v_fma_f32 v18, v45, v61, v138
	v_mul_f32_e32 v41, v18, v17
	v_lshlrev_b32_e32 v17, 16, v135
	v_fma_f32 v18, v46, v62, v138
	v_mul_f32_e32 v42, v18, v17
	v_and_b32_e32 v17, 0xffff0000, v135
	v_fma_f32 v18, v47, v63, v138
	v_mul_f32_e32 v43, v18, v17
	v_mul_f32_e32 v17, v41, v41
	v_mul_f32_e32 v18, v42, v42
	v_fmac_f32_e32 v17, v40, v40
	v_fmac_f32_e32 v18, v43, v43
	v_add_f32_e32 v17, v17, v18
	v_add_f32_e32 v16, v16, v17
	v_lshlrev_b32_e32 v17, 16, v132
	v_fma_f32 v18, v48, v68, v138
	v_mul_f32_e32 v44, v18, v17
	v_and_b32_e32 v17, 0xffff0000, v132
	v_fma_f32 v18, v49, v69, v138
	v_mul_f32_e32 v45, v18, v17
	v_lshlrev_b32_e32 v17, 16, v133
	v_fma_f32 v18, v50, v70, v138
	v_mul_f32_e32 v46, v18, v17
	v_and_b32_e32 v17, 0xffff0000, v133
	v_fma_f32 v18, v51, v71, v138
	v_mul_f32_e32 v47, v18, v17
	v_mul_f32_e32 v17, v45, v45
	v_mul_f32_e32 v18, v46, v46
	v_fmac_f32_e32 v17, v44, v44
	v_fmac_f32_e32 v18, v47, v47
	v_add_f32_e32 v17, v17, v18
	v_add_f32_e32 v16, v16, v17
	v_lshlrev_b32_e32 v17, 16, v130
	v_fma_f32 v18, v56, v76, v138
	v_mul_f32_e32 v48, v18, v17
	v_and_b32_e32 v17, 0xffff0000, v130
	v_fma_f32 v18, v57, v77, v138
	v_mul_f32_e32 v49, v18, v17
	v_lshlrev_b32_e32 v17, 16, v131
	v_fma_f32 v18, v58, v78, v138
	v_mul_f32_e32 v50, v18, v17
	v_and_b32_e32 v17, 0xffff0000, v131
	v_fma_f32 v18, v59, v79, v138
	v_mul_f32_e32 v51, v18, v17
	v_mul_f32_e32 v17, v49, v49
	v_mul_f32_e32 v18, v50, v50
	v_fmac_f32_e32 v17, v48, v48
	v_fmac_f32_e32 v18, v51, v51
	v_add_f32_e32 v17, v17, v18
	v_add_f32_e32 v16, v16, v17
	v_lshlrev_b32_e32 v17, 16, v128
	v_fma_f32 v18, v64, v80, v138
	v_mul_f32_e32 v52, v18, v17
	v_and_b32_e32 v17, 0xffff0000, v128
	v_fma_f32 v18, v65, v81, v138
	v_mul_f32_e32 v53, v18, v17
	v_lshlrev_b32_e32 v17, 16, v129
	v_fma_f32 v18, v66, v82, v138
	v_mul_f32_e32 v54, v18, v17
	v_and_b32_e32 v17, 0xffff0000, v129
	v_fma_f32 v18, v67, v83, v138
	v_mul_f32_e32 v55, v18, v17
	v_mul_f32_e32 v17, v53, v53
	v_mul_f32_e32 v18, v54, v54
	v_fmac_f32_e32 v17, v52, v52
	v_fmac_f32_e32 v18, v55, v55
	v_add_f32_e32 v17, v17, v18
	v_add_f32_e32 v16, v16, v17
	v_lshlrev_b32_e32 v17, 16, v126
	s_waitcnt lgkmcnt(0)
	v_fma_f32 v18, v72, v28, v138
	v_mul_f32_e32 v28, v18, v17
	v_and_b32_e32 v17, 0xffff0000, v126
	v_fma_f32 v18, v73, v29, v138
	v_mul_f32_e32 v29, v18, v17
	v_lshlrev_b32_e32 v17, 16, v127
	v_fma_f32 v18, v74, v30, v138
	v_mul_f32_e32 v30, v18, v17
	v_and_b32_e32 v17, 0xffff0000, v127
	v_fma_f32 v18, v75, v31, v138
	v_mul_f32_e32 v31, v18, v17
	v_mul_f32_e32 v17, v29, v29
	v_mul_f32_e32 v18, v30, v30
	v_fmac_f32_e32 v17, v28, v28
	v_fmac_f32_e32 v18, v31, v31
	v_add_f32_e32 v17, v17, v18
	v_add_f32_e32 v21, v16, v17
	ds_read_b128 v[16:19], v89 offset:448
	v_and_b32_e32 v22, 0xffff0000, v124
	v_lshlrev_b32_e32 v23, 16, v125
	s_and_b32 s27, s33, 0xffffff80
	v_add_u32_e32 v20, s27, v102
	s_waitcnt lgkmcnt(0)
	v_pk_mul_f32 v[18:19], v[26:27], v[18:19]
	v_pk_mul_f32 v[24:25], v[24:25], v[16:17]
	v_lshl_add_u32 v27, s36, 2, v143
	v_pk_mov_b32 v[16:17], v[24:25], v[18:19] op_sel:[1,0]
	v_mov_b32_e32 v25, v19
	v_pk_add_f32 v[16:17], v[138:139], v[16:17] op_sel_hi:[0,1]
	v_pk_mul_f32 v[16:17], v[16:17], v[22:23]
	v_lshlrev_b32_e32 v22, 16, v124
	v_and_b32_e32 v23, 0xffff0000, v125
	v_pk_add_f32 v[18:19], v[138:139], v[24:25] op_sel_hi:[0,1]
	v_pk_mul_f32 v[18:19], v[18:19], v[22:23]
	v_pk_mul_f32 v[22:23], v[16:17], v[16:17]
	s_lshl_b32 s98, s36, 1
	v_pk_fma_f32 v[22:23], v[18:19], v[18:19], v[22:23]
	v_lshlrev_b32_e32 v144, 1, v85
	v_add_f32_e32 v22, v22, v23
	v_and_b32_e32 v23, 64, v214
	v_add_f32_e32 v21, v21, v22
	v_xor_b32_e32 v22, 16, v214
	v_add_u32_e32 v23, 64, v23
	v_cmp_lt_i32_e32 vcc, v22, v23
	s_xor_b32 s35, s35, 1
	s_add_i32 s33, s33, 32
	v_cndmask_b32_e32 v22, v214, v22, vcc
	v_lshlrev_b32_e32 v22, 2, v22
	ds_bpermute_b32 v22, v22, v21
	s_addk_i32 s34, 0x80
	s_waitcnt lgkmcnt(0)
	v_add_f32_e32 v21, v21, v22
	v_xor_b32_e32 v22, 32, v214
	v_cmp_lt_i32_e32 vcc, v22, v23
	v_cndmask_b32_e32 v22, v214, v22, vcc
	v_lshlrev_b32_e32 v22, 2, v22
	ds_bpermute_b32 v22, v22, v21
	s_waitcnt lgkmcnt(0)
	v_add_f32_e32 v21, v21, v22
	v_fmamk_f32 v21, v21, 0x3c000000, v210
	v_cmp_gt_f32_e32 vcc, s89, v21
	v_mul_f32_e32 v22, 0x4b800000, v21
	s_nop 0
	v_cndmask_b32_e32 v21, v21, v22, vcc
	v_rsq_f32_e32 v21, v21
	s_nop 0
	v_mul_f32_e32 v22, 0x45800000, v21
	v_cndmask_b32_e32 v26, v21, v22, vcc
	ds_read_b128 v[22:25], v27
	v_mul_f32_e32 v32, v32, v26
	v_ashrrev_i32_e32 v21, 31, v20
	v_lshlrev_b64 v[20:21], 11, v[20:21]
	v_lshl_add_u64 v[20:21], s[44:45], 0, v[20:21]
	s_waitcnt lgkmcnt(0)
	v_mul_f32_e32 v22, v22, v32
	v_mul_f32_e32 v32, v33, v26
	v_mul_f32_e32 v23, v23, v32
	s_nop 0
	v_cvt_pk_bf16_f32 v22, v22, v23
	s_nop 1
	v_mul_f32_e32 v23, v34, v26
	v_mul_f32_e32 v23, v24, v23
	v_mul_f32_e32 v24, v35, v26
	v_lshl_add_u64 v[20:21], v[20:21], 0, s[98:99]
	v_mul_f32_e32 v24, v25, v24
	s_nop 0
	v_cvt_pk_bf16_f32 v23, v23, v24
	s_nop 1
	v_lshl_add_u64 v[24:25], v[20:21], 0, v[144:145]
	global_store_dwordx2 v[24:25], v[22:23], off
	ds_read_b128 v[20:23], v27 offset:64
	v_mul_f32_e32 v32, v36, v26
	v_mul_f32_e32 v28, v28, v26
	v_mul_f32_e32 v18, v18, v26
	v_mul_f32_e32 v16, v16, v26
	s_waitcnt lgkmcnt(0)
	v_mul_f32_e32 v20, v20, v32
	v_mul_f32_e32 v32, v37, v26
	v_mul_f32_e32 v21, v21, v32
	s_nop 0
	v_cvt_pk_bf16_f32 v20, v20, v21
	s_nop 1
	v_mul_f32_e32 v21, v38, v26
	v_mul_f32_e32 v21, v22, v21
	v_mul_f32_e32 v22, v39, v26
	v_mul_f32_e32 v22, v23, v22
	s_nop 0
	v_cvt_pk_bf16_f32 v21, v21, v22
	s_nop 1
	global_store_dwordx2 v[24:25], v[20:21], off offset:32
	ds_read_b128 v[20:23], v27 offset:128
	v_mul_f32_e32 v32, v40, v26
	v_mul_f32_e32 v17, v17, v26
	s_and_b64 vcc, exec, s[46:47]
	s_waitcnt lgkmcnt(0)
	v_mul_f32_e32 v20, v20, v32
	v_mul_f32_e32 v32, v41, v26
	v_mul_f32_e32 v21, v21, v32
	s_nop 0
	v_cvt_pk_bf16_f32 v20, v20, v21
	s_nop 1
	v_mul_f32_e32 v21, v42, v26
	v_mul_f32_e32 v21, v22, v21
	v_mul_f32_e32 v22, v43, v26
	v_mul_f32_e32 v22, v23, v22
	s_nop 0
	v_cvt_pk_bf16_f32 v21, v21, v22
	s_nop 1
	global_store_dwordx2 v[24:25], v[20:21], off offset:64
	ds_read_b128 v[20:23], v27 offset:192
	v_mul_f32_e32 v32, v44, v26
	s_waitcnt lgkmcnt(0)
	v_mul_f32_e32 v20, v20, v32
	v_mul_f32_e32 v32, v45, v26
	v_mul_f32_e32 v21, v21, v32
	s_nop 0
	v_cvt_pk_bf16_f32 v20, v20, v21
	s_nop 1
	v_mul_f32_e32 v21, v46, v26
	v_mul_f32_e32 v21, v22, v21
	v_mul_f32_e32 v22, v47, v26
	v_mul_f32_e32 v22, v23, v22
	s_nop 0
	v_cvt_pk_bf16_f32 v21, v21, v22
	s_nop 1
	global_store_dwordx2 v[24:25], v[20:21], off offset:96
	ds_read_b128 v[20:23], v27 offset:256
	v_mul_f32_e32 v32, v48, v26
	s_waitcnt lgkmcnt(0)
	v_mul_f32_e32 v20, v32, v20
	v_mul_f32_e32 v32, v49, v26
	v_mul_f32_e32 v21, v32, v21
	s_nop 0
	v_cvt_pk_bf16_f32 v20, v20, v21
	s_nop 1
	v_mul_f32_e32 v21, v50, v26
	v_mul_f32_e32 v21, v21, v22
	v_mul_f32_e32 v22, v51, v26
	v_mul_f32_e32 v22, v22, v23
	s_nop 0
	v_cvt_pk_bf16_f32 v21, v21, v22
	s_nop 1
	global_store_dwordx2 v[24:25], v[20:21], off offset:128
	ds_read_b128 v[20:23], v27 offset:320
	v_mul_f32_e32 v32, v52, v26
	s_waitcnt lgkmcnt(0)
	v_mul_f32_e32 v20, v32, v20
	v_mul_f32_e32 v32, v53, v26
	v_mul_f32_e32 v21, v32, v21
	s_nop 0
	v_cvt_pk_bf16_f32 v20, v20, v21
	s_nop 1
	v_mul_f32_e32 v21, v54, v26
	v_mul_f32_e32 v21, v21, v22
	v_mul_f32_e32 v22, v55, v26
	v_mul_f32_e32 v22, v22, v23
	s_nop 0
	v_cvt_pk_bf16_f32 v21, v21, v22
	s_nop 1
	global_store_dwordx2 v[24:25], v[20:21], off offset:160
	ds_read_b128 v[20:23], v27 offset:384
	s_waitcnt lgkmcnt(0)
	v_mul_f32_e32 v20, v28, v20
	v_mul_f32_e32 v28, v29, v26
	v_mul_f32_e32 v21, v28, v21
	s_nop 0
	v_cvt_pk_bf16_f32 v20, v20, v21
	s_nop 1
	v_mul_f32_e32 v21, v30, v26
	v_mul_f32_e32 v21, v21, v22
	v_mul_f32_e32 v22, v31, v26
	v_mul_f32_e32 v22, v22, v23
	s_nop 0
	v_cvt_pk_bf16_f32 v21, v21, v22
	s_nop 1
	global_store_dwordx2 v[24:25], v[20:21], off offset:192
	ds_read_b128 v[20:23], v27 offset:448
	s_waitcnt lgkmcnt(0)
	v_mul_f32_e32 v18, v18, v20
	v_mul_f32_e32 v16, v16, v21
	s_nop 0
	v_cvt_pk_bf16_f32 v16, v18, v16
	s_nop 1
	v_mul_f32_e32 v17, v17, v22
	v_mul_f32_e32 v18, v19, v26
	v_mul_f32_e32 v18, v18, v23
	s_nop 0
	v_cvt_pk_bf16_f32 v17, v17, v18
	s_nop 1
	global_store_dwordx2 v[24:25], v[16:17], off offset:224
	s_waitcnt vmcnt(8)
	v_mov_b64_e32 v[140:141], v[120:121]
	v_mov_b64_e32 v[136:137], v[118:119]
	v_mov_b64_e32 v[134:135], v[116:117]
	v_mov_b64_e32 v[132:133], v[114:115]
	v_mov_b64_e32 v[130:131], v[112:113]
	v_mov_b64_e32 v[128:129], v[110:111]
	v_mov_b64_e32 v[126:127], v[108:109]
	v_mov_b64_e32 v[124:125], v[106:107]
	v_mov_b64_e32 v[32:33], v[122:123]
	v_mov_b64_e32 v[30:31], v[6:7]
	v_mov_b64_e32 v[28:29], v[4:5]
	v_mov_b64_e32 v[26:27], v[2:3]
	v_mov_b64_e32 v[22:23], v[10:11]
	v_mov_b64_e32 v[18:19], v[14:15]
	v_mov_b64_e32 v[24:25], v[0:1]
	v_mov_b64_e32 v[20:21], v[8:9]
	v_mov_b64_e32 v[16:17], v[12:13]
	s_barrier
	s_cbranch_vccnz .LBB0_103
